# ret scan units raised to s_setprio 3 (equal to ssd) so the latency-bound ret chain is not starved
# baseline (speedup 1.0000x reference)
; __device__ __forceinline__ int tidx() { int t = threadIdx.x & 255; asm volatile("" : "+v"(t)); return t; }
; __device__ __forceinline__ int half_id() { int t = (int)(threadIdx.x >> 8); asm volatile("" : "+v"(t)); return __builtin_amdgcn_readfirstlane(t); }
; #define LAS3 __attribute__((address_space(3)))
; __device__ __forceinline__ void half_barrier(char* smem_half) {
;   const int h = half_id();
;   LAS3 unsigned* cnt = (LAS3 unsigned*)(smem_half + (2 - h) * 65536 + 8 + h * 4);
;   asm volatile("s_waitcnt lgkmcnt(0)" ::: "memory");
;   if ((tidx() & 63) == 0) {
;     const unsigned old = __hip_atomic_fetch_add(cnt, 1u, __ATOMIC_RELAXED, __HIP_MEMORY_SCOPE_WORKGROUP);
;     const unsigned target = (old & ~3u) + 4u;
;     while (__hip_atomic_load(cnt, __ATOMIC_RELAXED, __HIP_MEMORY_SCOPE_WORKGROUP) < target) __builtin_amdgcn_s_sleep(1);
;   }
; __device__ __forceinline__ void ret_mfma_unit(CP p, int l, int u, char* smem) {
;   const int tid = tidx(), wv = tid >> 6, lane = tid & 63, r = lane & 15, fq = lane >> 4;
;   const int bh = u * 2 + (wv >> 1), b = bh >> 2, h = bh & 3, eh = wv & 1;
;   char* wl = smem + wv * 8192;
;   bf16_t* KT = (bf16_t*)wl;
;   bf16_t* VT = (bf16_t*)(wl + 1024);
;   bf16_t* PT = (bf16_t*)(wl + 3072);
;   bf16_t* ST = (bf16_t*)(wl + 4096);
;   const bf16_t* proj = (const bf16_t*)(p.ws + WS_PROJ);
;   const float* rope = (const float*)(p.ws + WS_ROPE);
;   bf16_t* Y = (bf16_t*)(p.ws + WS_Y);
;   half_barrier(smem);
.LBB0_517:
	s_andn2_b64 vcc, exec, s[2:3]
	s_mov_b64 s[8:9], 0x1408
	s_mov_b64 s[34:35], 0x1508
	s_cbranch_vccnz .LBB0_526
	s_setprio 3
	s_waitcnt vmcnt(3)
	v_mov_b32_e32 v0, v214
	v_mov_b32_e32 v1, v213
	s_waitcnt lgkmcnt(0)
	s_nop 0
	v_readfirstlane_b32 s11, v1
	v_mov_b32_e32 v1, v214
	s_nop 0
	v_and_b32_e32 v1, 63, v1
	v_cmp_eq_u32_e32 vcc, 0, v1
	s_and_saveexec_b64 s[2:3], vcc
	s_cbranch_execz .LBB0_524
	s_mov_b64 s[4:5], exec
	s_lshl_b32 s10, s11, 16
	v_mbcnt_lo_u32_b32 v1, s4, 0
	s_sub_i32 s10, s63, s10
	v_mbcnt_hi_u32_b32 v1, s5, v1
	s_add_i32 s10, s10, 0x20000
	s_lshl_b32 s11, s11, 2
	v_cmp_eq_u32_e32 vcc, 0, v1
	s_and_saveexec_b64 s[12:13], vcc
	s_bcnt1_i32_b64 s4, s[4:5]
	s_add_i32 s5, s10, s11
	v_mov_b32_e32 v2, s5
	v_mov_b32_e32 v3, s4
	ds_add_rtn_u32 v2, v2, v3 offset:8
	s_or_b64 exec, exec, s[12:13]
	s_add_i32 s10, s10, s11
	s_waitcnt lgkmcnt(0)
	v_readfirstlane_b32 s4, v2
	v_mov_b32_e32 v2, s10
	ds_read_b32 v2, v2 offset:8
	v_add_u32_e32 v1, s4, v1
	v_and_b32_e32 v1, -4, v1
	v_add_u32_e32 v1, 4, v1
	s_waitcnt lgkmcnt(0)
	v_cmp_lt_u32_e32 vcc, v2, v1
	s_and_b64 exec, exec, vcc
	s_cbranch_execz .LBB0_524
	s_mov_b64 s[4:5], 0
